# grid barrier arrival: arrival atomic issued before the LDS census reads, generation tracked in a spill lane instead of integer division
# speedup vs baseline: 1.0070x; 1.0070x over previous
.LBB0_5:
	s_or_b64 exec, exec, s[4:5]
	s_load_dwordx2 s[10:11], s[0:1], 0x100
	s_waitcnt lgkmcnt(0)
	s_lshl_b32 s41, s10, 1
	s_lshl_b32 s40, s11, 1
	s_cmp_ge_i32 s41, s40
	s_cbranch_scc1 .LBB0_573
	s_add_u32 s20, s62, 0xc300000
	s_addc_u32 s21, s63, 0
	s_add_u32 s22, s62, 0xa280000
	s_addc_u32 s23, s63, 0
	v_readlane_b32 s33, v250, 0
	s_cmpk_lt_i32 s33, 0x596
	s_cselect_b64 s[4:5], -1, 0
	v_writelane_b32 v250, s4, 5
	s_load_dwordx16 s[80:95], s[0:1], 0x40
	v_mov_b32_e32 v2, 0x4ec
	v_writelane_b32 v250, s5, 6
	s_ashr_i32 s4, s33, 31
	v_writelane_b32 v250, s4, 7
	s_lshr_b32 s4, s4, 29
	s_add_i32 s4, s33, s4
	s_ashr_i32 s19, s4, 3
	s_and_b32 s4, s4, -8
	s_sub_i32 s26, s33, s4
	s_mul_i32 s13, s26, 0xb2
	s_add_i32 s13, s13, 6
	s_ashr_i32 s4, s24, 31
	s_cmpk_lt_i32 s33, 0x96
	v_writelane_b32 v250, s4, 8
	s_cselect_b64 s[4:5], -1, 0
	v_writelane_b32 v250, s4, 9
	s_add_i32 s6, s33, 0xffffff6a
	v_sub_co_u32_e32 v2, vcc, s33, v2
	v_writelane_b32 v250, s5, 10
	s_add_i32 s4, s33, 0x4ea
	s_cmpk_lt_i32 s4, 0x840
	s_cselect_b64 s[8:9], -1, 0
	v_writelane_b32 v250, s8, 11
	s_cmpk_lt_i32 s4, 0x2c0
	v_mov_b32_e32 v1, 0x3ec
	v_writelane_b32 v250, s9, 12
	s_cselect_b64 s[8:9], -1, 0
	v_writelane_b32 v250, s8, 13
	s_cmpk_gt_i32 s4, 0x2bf
	s_mov_b32 s97, 0
	v_writelane_b32 v250, s9, 14
	v_writelane_b32 v250, s4, 15
	s_cselect_b64 s[4:5], -1, 0
	v_writelane_b32 v250, s4, 16
	s_cmpk_lt_u32 s33, 0x356
	s_mov_b32 s96, s24
	v_writelane_b32 v250, s5, 17
	s_cselect_b64 s[4:5], -1, 0
	v_writelane_b32 v250, s4, 18
	v_mov_b32_e32 v161, 0x358637bd
	v_mov_b32_e32 v243, 1
	v_writelane_b32 v250, s5, 19
	s_add_u32 s4, s62, 0xad80000
	s_addc_u32 s5, s63, 0
	v_writelane_b32 v250, s4, 20
	v_mov_b64_e32 v[248:249], 0x71b
	v_mov_b64_e32 v[134:135], 0x71c
	v_writelane_b32 v250, s5, 21
	s_add_i32 s4, s24, 0xffffff6a
	s_cmpk_lt_u32 s6, 0x440
	v_writelane_b32 v250, s4, 22
	s_cselect_b64 s[4:5], -1, 0
	v_writelane_b32 v250, s4, 23
	s_add_u32 s44, s62, 0xe380000
	s_addc_u32 s45, s63, 0
	v_writelane_b32 v250, s5, 24
	s_lshr_b32 s4, s6, 4
	s_mul_hi_u32 s4, s4, 0x24924925
	s_mul_i32 s5, s4, 0xffffff90
	v_writelane_b32 v250, s6, 25
	s_add_i32 s5, s5, s6
	s_lshl_b32 s4, s4, 6
	v_writelane_b32 v250, s4, 26
	s_lshl_b32 s4, s5, 6
	s_ashr_i32 s5, s4, 31
	s_lshl_b64 s[4:5], s[4:5], 2
	s_waitcnt lgkmcnt(0)
	s_add_u32 s4, s90, s4
	s_addc_u32 s5, s91, s5
	v_writelane_b32 v250, s4, 27
	s_cmp_gt_i32 s26, -1
	v_mov_b64_e32 v[136:137], 0x595
	v_writelane_b32 v250, s5, 28
	s_cselect_b64 s[4:5], -1, 0
	v_writelane_b32 v250, s4, 29
	v_mov_b64_e32 v[138:139], 0x596
	v_mov_b32_e32 v166, 0x7f800000
	v_writelane_b32 v250, s5, 30
	s_add_i32 s4, s33, -16
	s_cmpk_lt_u32 s4, 0x2c0
	s_cselect_b64 s[6:7], -1, 0
	v_writelane_b32 v250, s6, 31
	s_cmpk_gt_u32 s4, 0x2bf
	v_mov_b32_e32 v140, 0x3f317218
	v_writelane_b32 v250, s7, 32
	s_cselect_b64 s[6:7], -1, 0
	v_writelane_b32 v250, s6, 33
	s_cmpk_gt_u32 s4, 0x57f
	s_mov_b64 s[46:47], 0x200000
	v_writelane_b32 v250, s7, 34
	s_cselect_b64 s[6:7], -1, 0
	v_writelane_b32 v250, s6, 35
	s_cmpk_lt_u32 s4, 0x840
	s_nop 0
	v_writelane_b32 v250, s7, 36
	v_writelane_b32 v250, s4, 37
	s_cselect_b64 s[4:5], -1, 0
	v_writelane_b32 v250, s4, 38
	s_nop 1
	v_writelane_b32 v250, s5, 39
	s_add_i32 s4, s33, 0xfffffa70
	v_writelane_b32 v250, s4, 40
	s_add_i32 s4, s33, 0xfffffd30
	v_writelane_b32 v250, s4, 41
	s_add_i32 s4, s24, -16
	s_cmp_gt_i32 s33, 43
	v_writelane_b32 v250, s4, 42
	s_cselect_b64 s[6:7], -1, 0
	s_add_i32 s4, s33, 0x414
	s_cmp_lt_i32 s4, 2.0
	s_cselect_b64 s[8:9], -1, 0
	s_cmpk_lt_i32 s4, 0x700
	s_cselect_b64 s[14:15], -1, 0
	v_writelane_b32 v250, s14, 43
	s_cmpk_gt_i32 s4, 0x6ff
	s_nop 0
	v_writelane_b32 v250, s15, 44
	v_writelane_b32 v250, s4, 45
	s_cselect_b64 s[4:5], -1, 0
	v_writelane_b32 v250, s4, 46
	s_nop 1
	v_writelane_b32 v250, s5, 47
	s_xor_b64 s[4:5], vcc, -1
	v_writelane_b32 v250, s4, 48
	s_nop 1
	v_writelane_b32 v250, s5, 49
	v_sub_co_u32_e64 v3, s[4:5], s33, v1
	v_mov_b32_e32 v1, 0x2c0
	s_nop 0
	v_writelane_b32 v250, s4, 50
	v_sub_co_u32_e32 v1, vcc, s33, v1
	s_nop 0
	v_writelane_b32 v250, s5, 51
	s_xor_b64 s[4:5], s[4:5], -1
	v_writelane_b32 v250, s4, 52
	s_cmpk_lt_u32 s33, 0x5ec
	s_nop 0
	v_writelane_b32 v250, s5, 53
	s_cselect_b64 s[4:5], -1, 0
	v_writelane_b32 v250, s4, 54
	s_nop 1
	v_writelane_b32 v250, s5, 55
	s_add_u32 s4, s62, 0xf580000
	s_addc_u32 s5, s63, 0
	v_writelane_b32 v250, s4, 56
	s_nop 1
	v_writelane_b32 v250, s5, 57
	s_add_u32 s4, s62, 0xf380000
	s_addc_u32 s5, s63, 0
	v_writelane_b32 v250, s4, 58
	s_nop 1
	v_writelane_b32 v250, s5, 59
	s_add_u32 s4, s62, 0xf180000
	s_addc_u32 s5, s63, 0
	v_writelane_b32 v250, s4, 60
	s_nop 1
	v_writelane_b32 v250, s5, 61
	s_add_i32 s4, s33, 0xfffffd14
	v_writelane_b32 v250, s4, 62
	s_sub_i32 s4, s24, 44
	v_writelane_b32 v250, s4, 63
	s_and_b32 s4, s33, 15
	s_add_u32 s14, s62, 0xf780000
	s_addc_u32 s15, s63, 0
	v_writelane_b32 v251, s14, 0
	s_lshr_b32 s5, s33, 1
	s_and_b32 s5, s5, 0x7ffffff8
	v_writelane_b32 v251, s15, 1
	v_writelane_b32 v251, s5, 2
	s_lshl_b32 s10, s4, 12
	s_lshl_b32 s4, s4, 6
	v_writelane_b32 v251, s4, 3
	s_lshr_b32 s4, s24, 4
	s_lshl_b32 s5, s4, 3
	s_add_u32 s14, s62, 0x2080000
	v_writelane_b32 v251, s5, 4
	s_addc_u32 s15, s63, 0
	v_writelane_b32 v251, s14, 5
	s_nop 1
	v_writelane_b32 v251, s15, 6
	s_add_u32 s14, s62, 0xfa88000
	s_addc_u32 s15, s63, 0
	v_writelane_b32 v251, s14, 7
	s_nop 1
	v_writelane_b32 v251, s15, 8
	s_add_u32 s14, s62, 0x6180000
	s_addc_u32 s15, s63, 0
	v_writelane_b32 v251, s14, 9
	s_nop 1
	v_writelane_b32 v251, s15, 10
	s_add_u32 s14, s62, 0xf7c0000
	s_addc_u32 s15, s63, 0
	s_add_i32 s4, s4, -4
	s_lshr_b32 s5, s33, 4
	v_writelane_b32 v251, s14, 11
	s_cmp_lt_i32 s5, s4
	s_nop 0
	v_writelane_b32 v251, s15, 12
	s_cselect_b64 s[14:15], -1, 0
	v_writelane_b32 v251, s14, 13
	s_sub_i32 s4, s5, s4
	s_lshl_b32 s4, s4, 1
	v_writelane_b32 v251, s15, 14
	v_writelane_b32 v251, s4, 15
	s_add_u32 s4, s62, 0xfa94000
	s_addc_u32 s5, s63, 0
	v_writelane_b32 v251, s4, 16
	s_cmpk_lt_i32 s33, 0x71c
	s_mul_i32 s14, s26, 0xe3
	v_writelane_b32 v251, s5, 17
	s_cselect_b64 s[4:5], -1, 0
	v_writelane_b32 v251, s4, 18
	s_add_i32 s14, s14, 4
	v_readfirstlane_b32 s15, v1
	v_writelane_b32 v251, s5, 19
	s_add_u32 s4, s62, 0x4100000
	s_addc_u32 s5, s63, 0
	v_writelane_b32 v251, s4, 20
	s_lshl_b32 s27, s33, 3
	s_lshl_b32 s28, s24, 3
	v_writelane_b32 v251, s5, 21
	s_add_u32 s4, s62, 0xfa70000
	s_addc_u32 s5, s63, 0
	v_writelane_b32 v251, s4, 22
	v_writelane_b32 v254, s27, 0
	s_nop 0
	v_writelane_b32 v251, s5, 23
	s_add_u32 s4, s62, 0x8200000
	s_addc_u32 s5, s63, 0
	v_writelane_b32 v251, s4, 24
	s_cmpk_lt_i32 s33, 0x150
	s_nop 0
	v_writelane_b32 v251, s5, 25
	s_cselect_b64 s[4:5], -1, 0
	v_writelane_b32 v251, s4, 26
	s_nop 1
	v_writelane_b32 v251, s5, 27
	s_lshl_b32 s4, s33, 9
	v_writelane_b32 v251, s4, 28
	s_add_u32 s4, s60, 0x4080000
	s_addc_u32 s5, s61, 0
	v_writelane_b32 v251, s4, 29
	s_nop 1
	v_writelane_b32 v251, s5, 30
	s_lshl_b32 s4, s24, 9
	v_writelane_b32 v251, s4, 31
	s_add_u32 s4, s62, 0xfb14000
	s_addc_u32 s5, s63, 0
	v_writelane_b32 v251, s4, 32
	s_nop 1
	v_writelane_b32 v251, s5, 33
	s_add_u32 s4, s60, 0x40b1000
	s_addc_u32 s5, s61, 0
	v_writelane_b32 v251, s4, 34
	s_lshl_b64 s[30:31], s[96:97], 9
	s_nop 0
	v_writelane_b32 v251, s5, 35
	s_mov_b32 s4, s33
	s_mov_b32 s5, s97
	s_lshl_b64 s[34:35], s[4:5], 9
	s_add_u32 s16, s62, 0xe400000
	s_addc_u32 s17, s63, 0
	v_writelane_b32 v251, s16, 36
	s_nop 1
	v_writelane_b32 v251, s17, 37
	s_add_u32 s16, s62, 0xe480000
	s_addc_u32 s17, s63, 0
	v_writelane_b32 v251, s16, 38
	s_nop 1
	v_writelane_b32 v251, s17, 39
	s_add_u32 s16, s62, 0xe500000
	s_addc_u32 s17, s63, 0
	v_writelane_b32 v251, s16, 40
	s_nop 1
	v_writelane_b32 v251, s17, 41
	s_add_u32 s16, s62, 0xe580000
	s_addc_u32 s17, s63, 0
	v_writelane_b32 v251, s16, 42
	s_nop 1
	v_writelane_b32 v251, s17, 43
	s_add_u32 s16, s62, 0xe600000
	s_addc_u32 s17, s63, 0
	v_writelane_b32 v251, s16, 44
	s_nop 1
	v_writelane_b32 v251, s17, 45
	s_add_u32 s16, s62, 0xe680000
	s_addc_u32 s17, s63, 0
	v_writelane_b32 v251, s16, 46
	s_nop 1
	v_writelane_b32 v251, s17, 47
	s_add_u32 s16, s62, 0xe700000
	s_addc_u32 s17, s63, 0
	v_writelane_b32 v251, s16, 48
	s_nop 1
	v_writelane_b32 v251, s17, 49
	s_add_u32 s16, s60, 0x4000000
	s_addc_u32 s17, s61, 0
	v_writelane_b32 v251, s16, 50
	s_cmpk_lt_u32 s33, 0x580
	s_nop 0
	v_writelane_b32 v251, s17, 51
	s_cselect_b64 s[16:17], -1, 0
	v_writelane_b32 v251, s16, 52
	s_nop 1
	v_writelane_b32 v251, s17, 53
	s_and_b64 s[16:17], vcc, exec
	s_cselect_b32 s29, s33, s15
	s_cselect_b32 s15, 1, 2
	v_writelane_b32 v251, s15, 54
	s_cselect_b32 s15, s81, s83
	v_writelane_b32 v251, s80, 55
	s_mul_hi_i32 s16, s29, 0x2e8ba2e9
	s_cselect_b32 s18, s80, s82
	v_writelane_b32 v252, s89, 0
	v_writelane_b32 v252, s90, 1
	v_writelane_b32 v252, s91, 2
	v_writelane_b32 v252, s92, 3
	v_writelane_b32 v252, s93, 4
	s_lshr_b32 s17, s16, 31
	s_ashr_i32 s16, s16, 3
	v_writelane_b32 v252, s94, 5
	s_add_i32 s16, s16, s17
	v_writelane_b32 v252, s95, 6
	s_mul_i32 s17, s16, 0xffffffd4
	v_writelane_b32 v252, s29, 7
	s_add_i32 s17, s17, s29
	s_lshl_b32 s16, s16, 6
	v_writelane_b32 v252, s16, 8
	s_lshl_b32 s16, s17, 6
	s_ashr_i32 s17, s16, 31
	s_lshl_b64 s[16:17], s[16:17], 2
	s_add_u32 s16, s18, s16
	s_addc_u32 s17, s15, s17
	v_writelane_b32 v252, s16, 9
	s_cmp_lt_i32 s11, 15
	v_writelane_b32 v251, s81, 56
	v_writelane_b32 v252, s17, 10
	s_cselect_b64 s[16:17], -1, 0
	v_writelane_b32 v252, s16, 11
	v_writelane_b32 v251, s82, 57
	v_writelane_b32 v251, s83, 58
	v_writelane_b32 v252, s17, 12
	s_add_u32 s16, s62, 0xfa90200
	s_addc_u32 s17, s63, 0
	v_writelane_b32 v252, s16, 13
	v_writelane_b32 v251, s84, 59
	v_writelane_b32 v251, s85, 60
	v_writelane_b32 v252, s17, 14
	s_add_u32 s16, s62, 0xfa90400
	s_addc_u32 s17, s63, 0
	v_writelane_b32 v252, s16, 15
	v_writelane_b32 v251, s86, 61
	v_writelane_b32 v251, s87, 62
	v_writelane_b32 v252, s17, 16
	s_add_u32 s16, s62, 0xfa90500
	s_addc_u32 s17, s63, 0
	v_writelane_b32 v252, s16, 17
	v_writelane_b32 v251, s88, 63
	s_nop 0
	v_writelane_b32 v252, s17, 18
	s_add_u32 s16, s62, 0xfa90600
	s_addc_u32 s17, s63, 0
	v_writelane_b32 v252, s16, 19
	s_nop 1
	v_writelane_b32 v252, s17, 20
	s_add_u32 s16, s62, 0xfa90700
	s_addc_u32 s17, s63, 0
	v_writelane_b32 v252, s16, 21
	s_nop 1
	v_writelane_b32 v252, s17, 22
	s_add_u32 s16, s62, 0xfa90800
	s_addc_u32 s17, s63, 0
	v_writelane_b32 v252, s16, 23
	s_nop 1
	v_writelane_b32 v252, s17, 24
	s_add_u32 s16, s62, 0xfa90900
	s_addc_u32 s17, s63, 0
	v_writelane_b32 v252, s16, 25
	s_nop 1
	v_writelane_b32 v252, s17, 26
	s_add_u32 s16, s62, 0xfa90a00
	s_addc_u32 s17, s63, 0
	v_writelane_b32 v252, s16, 27
	s_nop 1
	v_writelane_b32 v252, s17, 28
	s_add_u32 s16, s62, 0xfa90b00
	s_addc_u32 s17, s63, 0
	v_writelane_b32 v252, s16, 29
	s_nop 1
	v_writelane_b32 v252, s17, 30
	s_add_u32 s16, s62, 0xfa90c00
	s_addc_u32 s17, s63, 0
	v_writelane_b32 v252, s16, 31
	s_nop 1
	v_writelane_b32 v252, s17, 32
	s_add_u32 s16, s62, 0xfa90d00
	s_addc_u32 s17, s63, 0
	v_writelane_b32 v252, s16, 33
	s_nop 1
	v_writelane_b32 v252, s17, 34
	s_add_u32 s16, s62, 0xfa90e00
	s_addc_u32 s17, s63, 0
	v_writelane_b32 v252, s16, 35
	s_nop 1
	v_writelane_b32 v252, s17, 36
	s_add_u32 s16, s62, 0xfa90f00
	s_addc_u32 s17, s63, 0
	v_writelane_b32 v252, s16, 37
	s_nop 1
	v_writelane_b32 v252, s17, 38
	s_add_u32 s16, s62, 0xfa91000
	s_addc_u32 s17, s63, 0
	v_writelane_b32 v252, s16, 39
	s_nop 1
	v_writelane_b32 v252, s17, 40
	s_add_u32 s16, s62, 0xfa91100
	s_addc_u32 s17, s63, 0
	v_writelane_b32 v252, s16, 41
	s_nop 1
	v_writelane_b32 v252, s17, 42
	s_add_u32 s16, s62, 0xfa91200
	s_addc_u32 s17, s63, 0
	v_writelane_b32 v252, s16, 43
	s_nop 1
	v_writelane_b32 v252, s17, 44
	s_add_u32 s16, s62, 0xfa91300
	s_addc_u32 s17, s63, 0
	v_writelane_b32 v252, s16, 45
	s_cmp_eq_u32 s12, 15
	s_nop 0
	v_writelane_b32 v252, s17, 46
	s_cselect_b64 s[16:17], -1, 0
	v_writelane_b32 v252, s16, 47
	s_cmp_eq_u32 s12, 14
	s_nop 0
	v_writelane_b32 v252, s17, 48
	s_cselect_b64 s[16:17], -1, 0
	v_writelane_b32 v252, s16, 49
	s_cmp_eq_u32 s12, 13
	s_nop 0
	v_writelane_b32 v252, s17, 50
	s_cselect_b64 s[16:17], -1, 0
	v_writelane_b32 v252, s16, 51
	s_cmp_eq_u32 s12, 12
	s_nop 0
	v_writelane_b32 v252, s17, 52
	s_cselect_b64 s[16:17], -1, 0
	v_writelane_b32 v252, s16, 53
	s_cmp_eq_u32 s12, 11
	s_nop 0
	v_writelane_b32 v252, s17, 54
	s_cselect_b64 s[16:17], -1, 0
	v_writelane_b32 v252, s16, 55
	s_cmp_eq_u32 s12, 10
	s_nop 0
	v_writelane_b32 v252, s17, 56
	s_cselect_b64 s[16:17], -1, 0
	v_writelane_b32 v252, s16, 57
	s_cmp_eq_u32 s12, 9
	s_nop 0
	v_writelane_b32 v252, s17, 58
	s_cselect_b64 s[16:17], -1, 0
	v_writelane_b32 v252, s16, 59
	s_cmp_eq_u32 s12, 8
	s_nop 0
	v_writelane_b32 v252, s17, 60
	s_cselect_b64 s[16:17], -1, 0
	v_writelane_b32 v252, s16, 61
	s_cmp_eq_u32 s12, 7
	s_nop 0
	v_writelane_b32 v252, s17, 62
	s_cselect_b64 s[16:17], -1, 0
	v_writelane_b32 v252, s16, 63
	s_cmp_eq_u32 s12, 6
	s_nop 0
	v_writelane_b32 v253, s17, 0
	s_cselect_b64 s[16:17], -1, 0
	v_writelane_b32 v253, s16, 1
	s_cmp_eq_u32 s12, 5
	s_nop 0
	v_writelane_b32 v253, s17, 2
	s_cselect_b64 s[16:17], -1, 0
	v_writelane_b32 v253, s16, 3
	s_cmp_eq_u32 s12, 4
	s_nop 0
	v_writelane_b32 v253, s17, 4
	s_cselect_b64 s[16:17], -1, 0
	v_writelane_b32 v253, s16, 5
	s_cmp_eq_u32 s12, 3
	s_nop 0
	v_writelane_b32 v253, s17, 6
	s_cselect_b64 s[16:17], -1, 0
	v_writelane_b32 v253, s16, 7
	s_cmp_eq_u32 s12, 2
	s_nop 0
	v_writelane_b32 v253, s17, 8
	s_cselect_b64 s[16:17], -1, 0
	v_writelane_b32 v253, s16, 9
	s_cmp_eq_u32 s12, 1
	s_nop 0
	v_writelane_b32 v253, s17, 10
	s_cselect_b64 s[16:17], -1, 0
	v_writelane_b32 v253, s16, 11
	s_cmp_eq_u32 s12, 0
	s_nop 0
	v_writelane_b32 v253, s17, 12
	s_cselect_b64 s[16:17], -1, 0
	s_lshl_b32 s11, s12, 8
	s_add_u32 s2, s2, s11
	v_writelane_b32 v253, s16, 13
	s_addc_u32 s3, s3, 0
	s_nop 0
	v_writelane_b32 v253, s17, 14
	s_add_u32 s16, s2, 0x1400
	s_addc_u32 s17, s3, 0
	v_writelane_b32 v253, s16, 15
	s_add_u32 s2, s2, 0x2400
	s_addc_u32 s3, s3, 0
	v_writelane_b32 v253, s17, 16
	v_writelane_b32 v253, s2, 17
	s_nop 1
	v_writelane_b32 v253, s3, 18
	s_add_u32 s2, s62, 0xfa93400
	s_addc_u32 s3, s63, 0
	v_writelane_b32 v253, s2, 19
	s_nop 1
	v_writelane_b32 v253, s3, 20
	s_add_u32 s2, s62, 0xfa93500
	s_addc_u32 s3, s63, 0
	v_writelane_b32 v253, s2, 21
	s_cmp_lt_i32 s26, 6
	s_nop 0
	v_writelane_b32 v253, s3, 22
	s_mul_i32 s2, s26, 0xb3
	s_cselect_b32 s2, s2, s13
	s_add_i32 s2, s2, s19
	s_mul_hi_i32 s3, s2, 0x2e8ba2e9
	s_lshr_b32 s11, s3, 31
	s_ashr_i32 s3, s3, 5
	s_add_i32 s3, s3, s11
	s_mul_i32 s11, s3, 0xb0
	s_lshl_b32 s12, s3, 3
	s_sub_i32 s11, s2, s11
	s_sub_i32 s2, 0x41, s12
	s_min_u32 s13, s2, 8
	s_add_i32 s2, s33, 0xbffffff0
	s_cmp_gt_u32 s2, 0xbfffffff
	s_cselect_b64 s[2:3], -1, 0
	v_writelane_b32 v253, s2, 23
	v_cvt_f32_ubyte0_e32 v4, s13
	v_cvt_f32_i32_e32 v1, s11
	v_writelane_b32 v253, s3, 24
	s_and_b64 s[2:3], s[6:7], s[8:9]
	v_writelane_b32 v253, s2, 25
	s_cmp_lt_i32 s26, 4
	v_rcp_iflag_f32_e32 v5, v4
	v_writelane_b32 v253, s3, 26
	s_mul_i32 s2, s26, 0xe4
	s_cselect_b32 s2, s2, s14
	s_add_i32 s2, s2, s19
	s_mul_hi_i32 s3, s2, 0x92492493
	s_add_i32 s3, s3, s2
	s_lshr_b32 s6, s3, 31
	s_ashr_i32 s3, s3, 7
	s_add_i32 s3, s3, s6
	s_mul_i32 s6, s3, 0xe0
	s_lshl_b32 s15, s3, 3
	v_mul_f32_e32 v5, v1, v5
	s_sub_i32 s14, s2, s6
	s_sub_i32 s2, 0x41, s15
	v_trunc_f32_e32 v5, v5
	s_min_u32 s16, s2, 8
	s_ashr_i32 s2, s11, 30
	v_fma_f32 v1, -v5, v4, v1
	s_or_b32 s6, s2, 1
	v_cmp_ge_f32_e64 s[2:3], |v1|, v4
	v_cvt_i32_f32_e32 v1, v5
	s_and_b64 s[2:3], s[2:3], exec
	s_cselect_b32 s2, s6, 0
	v_writelane_b32 v253, s26, 27
	v_readfirstlane_b32 s3, v1
	s_add_i32 s2, s3, s2
	s_mul_i32 s3, s2, s13
	s_sub_i32 s3, s11, s3
	s_sext_i32_i16 s3, s3
	s_add_i32 s12, s12, s3
	v_writelane_b32 v253, s19, 28
	s_mov_b32 s8, s12
	s_ashr_i32 s13, s12, 31
	s_bfe_i64 s[6:7], s[2:3], 0x100000
	v_writelane_b32 v253, s8, 29
	s_lshl_b64 s[6:7], s[6:7], 19
	v_cvt_f32_ubyte0_e32 v4, s16
	v_writelane_b32 v253, s9, 30
	s_lshl_b64 s[8:9], s[12:13], 19
	s_add_u32 s6, s22, s6
	v_writelane_b32 v253, s22, 31
	s_addc_u32 s7, s23, s7
	s_add_u32 s8, s20, s8
	s_addc_u32 s9, s21, s9
	s_add_u32 s12, s6, 0x40000
	v_writelane_b32 v253, s23, 32
	s_addc_u32 s13, s7, 0
	v_writelane_b32 v253, s12, 33
	v_cvt_f32_i32_e32 v1, s14
	v_rcp_iflag_f32_e32 v5, v4
	v_writelane_b32 v253, s13, 34
	s_add_u32 s12, s8, 0x40000
	v_writelane_b32 v253, s8, 35
	s_addc_u32 s13, s9, 0
	v_mul_f32_e32 v5, v1, v5
	v_writelane_b32 v253, s9, 36
	v_writelane_b32 v253, s12, 37
	v_trunc_f32_e32 v5, v5
	s_add_u32 s8, s6, 0x40080
	v_writelane_b32 v253, s13, 38
	v_writelane_b32 v253, s6, 39
	v_fma_f32 v1, -v5, v4, v1
	s_addc_u32 s9, s7, 0
	v_writelane_b32 v253, s7, 40
	v_cmp_ge_f32_e64 s[6:7], |v1|, v4
	v_cvt_i32_f32_e32 v1, v5
	s_ashr_i32 s3, s14, 30
	s_or_b32 s3, s3, 1
	s_and_b64 s[6:7], s[6:7], exec
	s_cselect_b32 s3, s3, 0
	v_readfirstlane_b32 s6, v1
	s_add_i32 s6, s6, s3
	s_mul_i32 s3, s6, s16
	s_sub_i32 s3, s14, s3
	s_sext_i32_i16 s3, s3
	v_writelane_b32 v253, s8, 41
	s_add_i32 s14, s15, s3
	s_mov_b32 s12, s14
	v_writelane_b32 v253, s9, 42
	s_ashr_i32 s15, s14, 31
	s_bfe_i64 s[8:9], s[6:7], 0x100000
	v_writelane_b32 v253, s12, 43
	s_load_dword s7, s[0:1], 0x110
	s_lshl_b64 s[8:9], s[8:9], 19
	v_writelane_b32 v253, s13, 44
	s_lshl_b64 s[12:13], s[14:15], 19
	s_add_u32 s8, s44, s8
	s_addc_u32 s9, s45, s9
	s_add_u32 s12, s20, s12
	v_writelane_b32 v253, s20, 45
	s_mul_i32 s3, s25, s24
	s_waitcnt lgkmcnt(0)
	s_mul_i32 s3, s3, s7
	v_writelane_b32 v253, s21, 46
	v_writelane_b32 v253, s3, 47
	s_sext_i32_i16 s2, s2
	s_addc_u32 s13, s21, s13
	v_writelane_b32 v253, s2, 48
	s_sext_i32_i16 s2, s6
	v_writelane_b32 v253, s2, 49
	s_add_u32 s2, s8, 0x40000
	s_addc_u32 s3, s9, 0
	v_writelane_b32 v253, s2, 50
	v_lshrrev_b32_e32 v1, 20, v0
	v_lshrrev_b32_e32 v0, 10, v0
	v_writelane_b32 v253, s3, 51
	s_add_u32 s2, s12, 0x40000
	v_writelane_b32 v253, s12, 52
	s_addc_u32 s3, s13, 0
	v_or_b32_e32 v0, v0, v1
	v_writelane_b32 v253, s13, 53
	v_writelane_b32 v253, s2, 54
	v_mov_b32_e32 v1, 0
	s_nop 0
	v_writelane_b32 v253, s3, 55
	s_add_u32 s2, s8, 0x40080
	v_writelane_b32 v253, s8, 56
	s_addc_u32 s3, s9, 0
	s_nop 0
	v_writelane_b32 v253, s9, 57
	v_writelane_b32 v253, s2, 58
	s_nop 1
	v_writelane_b32 v253, s3, 59
	s_add_i32 s2, s33, s24
	s_add_i32 s3, s2, 0xfffffa60
	v_writelane_b32 v253, s3, 60
	s_addk_i32 s2, 0xfae8
	v_writelane_b32 v253, s2, 61
	s_add_u32 s2, s62, 0x8300600
	s_addc_u32 s3, s63, 0
	v_writelane_b32 v253, s2, 62
	s_nop 1
	v_writelane_b32 v253, s3, 63
	s_add_i32 s2, s27, 0xffffc000
	v_writelane_b32 v254, s2, 1
	s_add_u32 s2, s62, 0xf7de000
	s_addc_u32 s3, s63, 0
	v_writelane_b32 v254, s2, 2
	s_mov_b64 s[26:27], 0x80
	s_nop 0
	v_writelane_b32 v254, s3, 3
	s_add_u32 s2, s62, 0x4101800
	s_addc_u32 s3, s63, 0
	v_writelane_b32 v254, s2, 4
	s_lshl_b64 s[4:5], s[4:5], 13
	s_nop 0
	v_writelane_b32 v254, s3, 5
	s_lshl_b32 s2, s33, 12
	v_writelane_b32 v254, s2, 6
	s_lshl_b32 s2, s24, 12
	v_writelane_b32 v254, s2, 7
	s_add_u32 s2, s60, s4
	s_addc_u32 s3, s61, s5
	v_writelane_b32 v254, s2, 8
	s_nop 1
	v_writelane_b32 v254, s3, 9
	s_lshl_b64 s[2:3], s[96:97], 15
	v_writelane_b32 v254, s2, 10
	s_nop 1
	v_writelane_b32 v254, s3, 11
	s_lshl_b64 s[2:3], s[96:97], 10
	s_add_u32 s6, s2, s34
	v_writelane_b32 v254, s2, 12
	s_addc_u32 s7, s3, s35
	s_nop 0
	v_writelane_b32 v254, s3, 13
	s_lshl_b64 s[2:3], s[96:97], 14
	s_add_u32 s2, s2, s4
	s_addc_u32 s3, s3, s5
	v_writelane_b32 v254, s6, 14
	s_add_u32 s2, s62, s2
	s_addc_u32 s3, s63, s3
	v_writelane_b32 v254, s7, 15
	v_writelane_b32 v254, s2, 16
	s_nop 1
	v_writelane_b32 v254, s3, 17
	s_mul_hi_u32 s3, s24, 0x600
	s_mul_i32 s2, s24, 0x600
	s_add_u32 s6, s2, s34
	v_writelane_b32 v254, s2, 18
	s_addc_u32 s7, s3, s35
	s_nop 0
	v_writelane_b32 v254, s3, 19
	s_mul_i32 s2, s24, 0x6000
	s_add_u32 s2, s2, s4
	s_mul_hi_u32 s3, s24, 0x6000
	s_addc_u32 s3, s3, s5
	v_writelane_b32 v254, s6, 20
	s_add_u32 s2, s62, s2
	s_addc_u32 s3, s63, s3
	v_writelane_b32 v254, s7, 21
	v_writelane_b32 v254, s2, 22
	s_nop 1
	v_writelane_b32 v254, s3, 23
	s_add_u32 s2, s34, s30
	v_writelane_b32 v254, s30, 24
	s_nop 1
	v_writelane_b32 v254, s31, 25
	v_writelane_b32 v254, s34, 26
	s_addc_u32 s3, s35, s31
	s_lshl_b64 s[6:7], s[96:97], 13
	v_writelane_b32 v254, s35, 27
	v_writelane_b32 v254, s2, 28
	s_mov_b32 s34, 0xbfb8aa3b
	s_nop 0
	v_writelane_b32 v254, s3, 29
	s_add_u32 s2, s4, s6
	v_writelane_b32 v254, s6, 30
	s_addc_u32 s3, s5, s7
	s_add_u32 s2, s62, s2
	v_writelane_b32 v254, s7, 31
	s_addc_u32 s3, s63, s3
	v_writelane_b32 v254, s2, 32
	s_nop 1
	v_writelane_b32 v254, s3, 33
	s_movk_i32 s2, 0x3ff
	v_and_or_b32 v0, v0, s2, v160
	s_add_u32 s2, s62, s4
	v_writelane_b32 v254, s4, 34
	s_addc_u32 s3, s63, s5
	s_nop 0
	v_writelane_b32 v254, s5, 35
	v_writelane_b32 v254, s2, 36
	s_nop 1
	v_writelane_b32 v254, s3, 37
	s_lshl_b32 s3, s33, 2
	s_mov_b32 s2, s97
	v_writelane_b32 v254, s2, 38
	s_nop 1
	v_writelane_b32 v254, s3, 39
	s_lshl_b32 s3, s24, 2
	s_mov_b32 s2, s97
	v_writelane_b32 v254, s2, 40
	s_nop 1
	v_writelane_b32 v254, s3, 41
	s_add_u32 s2, s60, 0x2000000
	s_addc_u32 s3, s61, 0
	v_writelane_b32 v254, s2, 42
	s_ashr_i32 s29, s28, 31
	s_nop 0
	v_writelane_b32 v254, s3, 43
	s_lshl_b32 s2, s10, 1
	v_writelane_b32 v254, s2, 44
	v_readfirstlane_b32 s2, v3
	s_load_dwordx16 s[80:95], s[0:1], 0x0
	s_load_dwordx16 s[4:19], s[0:1], 0x80
	v_writelane_b32 v254, s2, 45
	v_readfirstlane_b32 s2, v2
	s_mov_b32 s0, s24
	s_nop 0
	v_writelane_b32 v254, s2, 46
	s_lshl_b32 s2, s33, 15
	v_writelane_b32 v254, s2, 47
	s_lshl_b32 s2, s24, 15
	v_writelane_b32 v254, s2, 48
	s_add_i32 s2, 0, 0x16000
	v_writelane_b32 v254, s2, 49
	s_add_i32 s2, 0, 0x20004
	v_writelane_b32 v254, s2, 50
	v_cmp_eq_u32_e64 s[2:3], 0, v0
	s_nop 1
	v_writelane_b32 v254, s2, 51
	s_nop 1
	v_writelane_b32 v254, s3, 52
	s_lshl_b64 s[2:3], s[96:97], 12
	v_writelane_b32 v254, s2, 53
	s_nop 1
	v_writelane_b32 v254, s3, 54
	s_lshl_b64 s[2:3], s[28:29], 2
	v_writelane_b32 v254, s2, 55
	s_nop 1
	v_writelane_b32 v254, s3, 56
	s_mov_b32 s2, s28
	v_writelane_b32 v254, s2, 57
	s_nop 1
	v_writelane_b32 v254, s3, 58
	s_lshl_b64 s[2:3], s[28:29], 11
	v_writelane_b32 v254, s2, 59
	s_nop 1
	v_writelane_b32 v254, s3, 60
	v_writelane_b32 v254, s0, 61
	s_nop 1
	v_writelane_b32 v254, s1, 62
	v_writelane_b32 v254, s40, 63
	s_mov_b32 s2, 0
	v_writelane_b32 v255, s2, 21
	s_cmp_eq_u32 s24, 0x100
	s_cselect_b32 s2, 1, 0
	v_writelane_b32 v255, s2, 20
	s_cbranch_scc0 .Lopt_off
	v_mov_b64_e32 v[134:135], 0x700
	v_mov_b64_e32 v[248:249], 0x6ff

.Lxb_noinv:
	s_mov_b64 s[0:1], exec
	v_readlane_b32 s2, v250, 3
	v_readlane_b32 s3, v250, 4
	s_and_b64 s[2:3], s[0:1], s[2:3]
	s_mov_b64 exec, s[2:3]
	s_cbranch_execz .LBB0_558
	v_readlane_b32 s20, v253, 15
	v_readlane_b32 s21, v253, 16
	s_add_i32 s28, 0, 0x20000
	v_mov_b32_e32 v0, s28
	s_waitcnt vmcnt(0) expcnt(0) lgkmcnt(0)
	s_nop 1
	global_atomic_add v18, v1, v243, s[20:21] sc0
	ds_read_b32 v3, v0
	v_readlane_b32 s2, v254, 50
	s_waitcnt lgkmcnt(0)
	v_cmp_ne_u32_e32 vcc, 0, v3
	v_mov_b32_e32 v0, s2
	ds_read_b32 v2, v0
	s_cbranch_vccnz .LBB0_522
	s_mov_b32 s29, 1
	s_branch .LBB0_510

.LBB0_522:
	s_waitcnt vmcnt(0)
	v_readfirstlane_b32 s2, v18
	v_readfirstlane_b32 s3, v3
	v_readlane_b32 s22, v255, 21
	s_add_i32 s2, s2, 1
	s_add_i32 s23, s22, 1
	s_mul_i32 s3, s3, s23
	v_writelane_b32 v255, s23, 21
	v_mov_b32_e32 v0, s22
	s_cmp_lg_u32 s2, s3
	s_cbranch_scc1 .Lxb_poll
	s_cmp_eq_u32 s41, 1
	s_cbranch_scc1 .Lxb_wb
	s_cmp_eq_u32 s41, 7
	s_cbranch_scc1 .Lxb_wb
	s_cmp_eq_u32 s41, 11
	s_cbranch_scc1 .Lxb_wb
	s_cmp_eq_u32 s41, 21
	s_cbranch_scc0 .Lxb_nowb
